# v2 + attention FOX/DIFF unit prologue: the serialized Q-row loads (load, vmcnt(0), unpack, repeat) are issued together into distinct registers with counted waits
# speedup vs baseline: 1.0140x; 1.0029x over previous
.LBB0_306:
	v_mov_b32_e32 v36, v223
	s_lshl_b32 s92, s12, 7
	v_ashrrev_i32_e32 v37, 31, v36
	v_lshl_add_u64 v[36:37], s[54:55], 0, v[36:37]
	v_lshlrev_b64 v[36:37], 8, v[36:37]
	v_lshl_add_u64 v[36:37], s[60:61], 0, v[36:37]
	v_lshl_add_u64 v[36:37], v[36:37], 0, s[92:93]
	v_lshl_add_u64 v[36:37], v[36:37], 0, v[34:35]
	global_load_dwordx4 v[38:41], v[36:37], off
	global_load_dwordx4 v[132:135], v[36:37], off offset:32
	global_load_dwordx4 v[136:139], v[36:37], off offset:64
	global_load_dwordx4 v[140:143], v[36:37], off offset:96
	v_add_u32_e32 v147, s84, v226
	s_mov_b32 s10, 0xf800000
	s_waitcnt vmcnt(3)
	v_lshlrev_b32_e32 v84, 16, v38
	v_and_b32_e32 v82, 0xffff0000, v38
	v_lshlrev_b32_e32 v80, 16, v39
	v_and_b32_e32 v78, 0xffff0000, v39
	v_lshlrev_b32_e32 v83, 16, v40
	v_and_b32_e32 v81, 0xffff0000, v40
	v_lshlrev_b32_e32 v79, 16, v41
	v_and_b32_e32 v77, 0xffff0000, v41
	v_mul_f32_e32 v42, v82, v82
	v_fmac_f32_e32 v42, v84, v84
	v_fmac_f32_e32 v42, v80, v80
	v_fmac_f32_e32 v42, v78, v78
	v_fmac_f32_e32 v42, v83, v83
	v_fmac_f32_e32 v42, v81, v81
	v_fmac_f32_e32 v42, v79, v79
	v_fmac_f32_e32 v42, v77, v77
	s_waitcnt vmcnt(2)
	v_lshlrev_b32_e32 v76, 16, v132
	v_and_b32_e32 v74, 0xffff0000, v132
	v_lshlrev_b32_e32 v72, 16, v133
	v_and_b32_e32 v70, 0xffff0000, v133
	v_lshlrev_b32_e32 v75, 16, v134
	v_and_b32_e32 v73, 0xffff0000, v134
	v_lshlrev_b32_e32 v71, 16, v135
	v_and_b32_e32 v69, 0xffff0000, v135
	v_fmac_f32_e32 v42, v76, v76
	v_fmac_f32_e32 v42, v74, v74
	v_fmac_f32_e32 v42, v72, v72
	v_fmac_f32_e32 v42, v70, v70
	v_fmac_f32_e32 v42, v75, v75
	v_fmac_f32_e32 v42, v73, v73
	v_fmac_f32_e32 v42, v71, v71
	v_fmac_f32_e32 v42, v69, v69
	s_waitcnt vmcnt(1)
	v_lshlrev_b32_e32 v68, 16, v136
	v_and_b32_e32 v66, 0xffff0000, v136
	v_lshlrev_b32_e32 v64, 16, v137
	v_and_b32_e32 v62, 0xffff0000, v137
	v_fmac_f32_e32 v42, v68, v68
	v_fmac_f32_e32 v42, v66, v66
	v_fmac_f32_e32 v42, v64, v64
	v_lshlrev_b32_e32 v67, 16, v138
	v_fmac_f32_e32 v42, v62, v62
	v_and_b32_e32 v65, 0xffff0000, v138
	v_fmac_f32_e32 v42, v67, v67
	v_lshlrev_b32_e32 v63, 16, v139
	v_fmac_f32_e32 v42, v65, v65
	v_and_b32_e32 v61, 0xffff0000, v139
	v_fmac_f32_e32 v42, v63, v63
	v_fmac_f32_e32 v42, v61, v61
	s_waitcnt vmcnt(0)
	v_lshlrev_b32_e32 v60, 16, v140
	v_and_b32_e32 v58, 0xffff0000, v140
	v_fmac_f32_e32 v42, v60, v60
	v_lshlrev_b32_e32 v56, 16, v141
	v_fmac_f32_e32 v42, v58, v58
	v_and_b32_e32 v53, 0xffff0000, v141
	v_fmac_f32_e32 v42, v56, v56
	v_lshlrev_b32_e32 v59, 16, v142
	v_fmac_f32_e32 v42, v53, v53
	v_and_b32_e32 v57, 0xffff0000, v142
	v_fmac_f32_e32 v42, v59, v59
	v_lshlrev_b32_e32 v55, 16, v143
	v_fmac_f32_e32 v42, v57, v57
	v_and_b32_e32 v52, 0xffff0000, v143
	v_fmac_f32_e32 v42, v55, v55
	v_fmac_f32_e32 v42, v52, v52
	v_mov_b32_e32 v36, v42
	s_nop 1
	v_permlane32_swap_b32_e32 v42, v36
	v_add_f32_e32 v36, v42, v36
	v_fmamk_f32 v36, v36, 0x3c800000, v214
	v_rsq_f32_e32 v36, v36
	s_nop 0
	v_mul_f32_e32 v54, 0x3e38aa3b, v36
	global_load_dwordx4 v[36:39], v[206:207], off offset:16
	global_load_dwordx4 v[44:47], v[206:207], off
	global_load_dwordx4 v[40:43], v[208:209], off offset:16
	global_load_dwordx4 v[48:51], v[208:209], off
	s_waitcnt vmcnt(3)
	v_mul_f32_e32 v36, v36, v54
	s_waitcnt vmcnt(2)
	v_mul_f32_e32 v44, v44, v54
	s_waitcnt vmcnt(1)
	v_mul_f32_e32 v36, v40, v36
	v_mul_f32_e32 v40, v36, v83
	v_mul_f32_e32 v36, v45, v54
	s_waitcnt vmcnt(0)
	v_mul_f32_e32 v36, v49, v36
	v_mul_f32_e32 v45, v36, v82
	v_mul_f32_e32 v36, v37, v54
	v_mul_f32_e32 v36, v41, v36
	v_mul_f32_e32 v37, v36, v81
	v_mul_f32_e32 v36, v46, v54
	v_mul_f32_e32 v36, v50, v36
	v_mul_f32_e32 v41, v36, v80
	v_mul_f32_e32 v36, v38, v54
	v_mul_f32_e32 v36, v42, v36
	v_mul_f32_e32 v42, v36, v79
	v_mul_f32_e32 v36, v47, v54
	v_mul_f32_e32 v36, v51, v36
	v_mul_f32_e32 v46, v36, v78
	v_mul_f32_e32 v36, v39, v54
	v_mul_f32_e32 v44, v48, v44
	v_mul_f32_e32 v36, v43, v36
	v_mul_f32_e32 v44, v44, v84
	v_mul_f32_e32 v43, v36, v77
	v_mul_f32_e32 v36, v45, v45
	v_fmac_f32_e32 v36, v44, v44
	v_fmac_f32_e32 v36, v41, v41
	v_fmac_f32_e32 v36, v46, v46
	v_fmac_f32_e32 v36, v40, v40
	v_fmac_f32_e32 v36, v37, v37
	v_fmac_f32_e32 v36, v42, v42
	v_cvt_pk_bf16_f32 v38, v44, v45
	v_cvt_pk_bf16_f32 v39, v41, v46
	v_cvt_pk_bf16_f32 v40, v40, v37
	v_cvt_pk_bf16_f32 v41, v42, v43
	ds_write_b128 v147, v[38:41]
	v_fmac_f32_e32 v36, v43, v43
	global_load_dwordx4 v[38:41], v[206:207], off offset:80
	global_load_dwordx4 v[42:45], v[206:207], off offset:64
	global_load_dwordx4 v[46:49], v[208:209], off offset:80
	global_load_dwordx4 v[78:81], v[208:209], off offset:64
	s_waitcnt vmcnt(3)
	v_mul_f32_e32 v38, v54, v38
	s_waitcnt vmcnt(2)
	v_mul_f32_e32 v37, v54, v42
	s_waitcnt vmcnt(1)
	v_mul_f32_e32 v38, v38, v46
	v_mul_f32_e32 v39, v54, v39
	s_waitcnt vmcnt(0)
	v_mul_f32_e32 v37, v37, v78
	v_mul_f32_e32 v42, v38, v75
	v_mul_f32_e32 v38, v54, v43
	v_mul_f32_e32 v39, v39, v47
	v_mul_f32_e32 v40, v54, v40
	v_mul_f32_e32 v37, v37, v76
	v_mul_f32_e32 v38, v38, v79
	v_mul_f32_e32 v43, v39, v73
	v_mul_f32_e32 v39, v54, v44
	v_mul_f32_e32 v40, v40, v48
	v_mul_f32_e32 v38, v38, v74
	v_mul_f32_e32 v39, v39, v80
	v_mul_f32_e32 v44, v40, v71
	v_mul_f32_e32 v40, v54, v45
	v_fmac_f32_e32 v36, v37, v37
	v_mul_f32_e32 v39, v39, v72
	v_mul_f32_e32 v40, v40, v81
	v_fmac_f32_e32 v36, v38, v38
	v_mul_f32_e32 v40, v40, v70
	v_fmac_f32_e32 v36, v39, v39
	v_fmac_f32_e32 v36, v40, v40
	v_mul_f32_e32 v41, v54, v41
	v_fmac_f32_e32 v36, v42, v42
	v_mul_f32_e32 v41, v41, v49
	v_fmac_f32_e32 v36, v43, v43
	v_mul_f32_e32 v41, v41, v69
	v_fmac_f32_e32 v36, v44, v44
	v_fmac_f32_e32 v36, v41, v41
	v_cvt_pk_bf16_f32 v38, v37, v38
	v_cvt_pk_bf16_f32 v39, v39, v40
	v_cvt_pk_bf16_f32 v40, v42, v43
	v_cvt_pk_bf16_f32 v41, v44, v41
	ds_write_b128 v147, v[38:41] offset:1024
	global_load_dwordx4 v[38:41], v[206:207], off offset:144
	global_load_dwordx4 v[42:45], v[206:207], off offset:128
	global_load_dwordx4 v[46:49], v[208:209], off offset:144
	global_load_dwordx4 v[70:73], v[208:209], off offset:128
	s_waitcnt vmcnt(3)
	v_mul_f32_e32 v38, v54, v38
	s_waitcnt vmcnt(2)
	v_mul_f32_e32 v37, v54, v42
	s_waitcnt vmcnt(1)
	v_mul_f32_e32 v38, v38, v46
	v_mul_f32_e32 v39, v54, v39
	s_waitcnt vmcnt(0)
	v_mul_f32_e32 v37, v37, v70
	v_mul_f32_e32 v42, v38, v67
	v_mul_f32_e32 v38, v54, v43
	v_mul_f32_e32 v39, v39, v47
	v_mul_f32_e32 v40, v54, v40
	v_mul_f32_e32 v37, v37, v68
	v_mul_f32_e32 v38, v38, v71
	v_mul_f32_e32 v43, v39, v65
	v_mul_f32_e32 v39, v54, v44
	v_mul_f32_e32 v40, v40, v48
	v_mul_f32_e32 v38, v38, v66
	v_mul_f32_e32 v39, v39, v72
	v_mul_f32_e32 v44, v40, v63
	v_mul_f32_e32 v40, v54, v45
	v_fmac_f32_e32 v36, v37, v37
	v_mul_f32_e32 v39, v39, v64
	v_mul_f32_e32 v40, v40, v73
	v_fmac_f32_e32 v36, v38, v38
	v_mul_f32_e32 v40, v40, v62
	v_fmac_f32_e32 v36, v39, v39
	v_fmac_f32_e32 v36, v40, v40
	v_mul_f32_e32 v41, v54, v41
	v_fmac_f32_e32 v36, v42, v42
	v_mul_f32_e32 v41, v41, v49
	v_fmac_f32_e32 v36, v43, v43
	v_mul_f32_e32 v41, v41, v61
	v_fmac_f32_e32 v36, v44, v44
	v_fmac_f32_e32 v36, v41, v41
	v_cvt_pk_bf16_f32 v38, v37, v38
	v_cvt_pk_bf16_f32 v39, v39, v40
	v_cvt_pk_bf16_f32 v40, v42, v43
	v_cvt_pk_bf16_f32 v41, v44, v41
	ds_write_b128 v147, v[38:41] offset:2048
	global_load_dwordx4 v[38:41], v[206:207], off offset:208
	global_load_dwordx4 v[42:45], v[206:207], off offset:192
	global_load_dwordx4 v[46:49], v[208:209], off offset:208
	global_load_dwordx4 v[62:65], v[208:209], off offset:192
	s_waitcnt vmcnt(3)
	v_mul_f32_e32 v38, v54, v38
	s_waitcnt vmcnt(2)
	v_mul_f32_e32 v37, v54, v42
	s_waitcnt vmcnt(1)
	v_mul_f32_e32 v38, v38, v46
	v_mul_f32_e32 v39, v54, v39
	s_waitcnt vmcnt(0)
	v_mul_f32_e32 v37, v37, v62
	v_mul_f32_e32 v42, v38, v59
	v_mul_f32_e32 v38, v54, v43
	v_mul_f32_e32 v39, v39, v47
	v_mul_f32_e32 v40, v54, v40
	v_mul_f32_e32 v37, v37, v60
	v_mul_f32_e32 v38, v38, v63
	v_mul_f32_e32 v43, v39, v57
	v_mul_f32_e32 v39, v54, v44
	v_mul_f32_e32 v40, v40, v48
	v_mul_f32_e32 v38, v38, v58
	v_mul_f32_e32 v39, v39, v64
	v_mul_f32_e32 v44, v40, v55
	v_mul_f32_e32 v40, v54, v45
	v_fmac_f32_e32 v36, v37, v37
	v_mul_f32_e32 v39, v39, v56
	v_mul_f32_e32 v40, v40, v65
	v_fmac_f32_e32 v36, v38, v38
	v_mul_f32_e32 v40, v40, v53
	v_fmac_f32_e32 v36, v39, v39
	v_fmac_f32_e32 v36, v40, v40
	v_mul_f32_e32 v41, v54, v41
	v_fmac_f32_e32 v36, v42, v42
	v_mul_f32_e32 v41, v41, v49
	v_fmac_f32_e32 v36, v43, v43
	v_mul_f32_e32 v41, v41, v52
	v_fmac_f32_e32 v36, v44, v44
	v_fmac_f32_e32 v36, v41, v41
	v_cvt_pk_bf16_f32 v38, v37, v38
	v_mov_b32_e32 v37, v36
	s_nop 1
	v_permlane32_swap_b32_e32 v36, v37
	v_add_f32_e32 v36, v36, v37
	v_cmp_gt_f32_e32 vcc, s10, v36
	v_mul_f32_e32 v37, 0x4f800000, v36
	v_cvt_pk_bf16_f32 v39, v39, v40
	v_cvt_pk_bf16_f32 v40, v42, v43
	v_cvt_pk_bf16_f32 v41, v44, v41
	ds_write_b128 v147, v[38:41] offset:3072
	v_cndmask_b32_e32 v36, v36, v37, vcc
	v_sqrt_f32_e32 v37, v36
	s_nop 0
	v_add_u32_e32 v38, -1, v37
	v_fma_f32 v39, -v38, v37, v36
	v_cmp_ge_f32_e64 s[42:43], 0, v39
	v_add_u32_e32 v39, 1, v37
	s_nop 0
	v_cndmask_b32_e64 v38, v37, v38, s[42:43]
	v_fma_f32 v37, -v39, v37, v36
	v_cmp_lt_f32_e64 s[42:43], 0, v37
	s_nop 1
	v_cndmask_b32_e64 v37, v38, v39, s[42:43]
	v_mul_f32_e32 v38, 0x37800000, v37
	v_cndmask_b32_e32 v37, v37, v38, vcc
	v_cmp_class_f32_e32 vcc, v36, v215
	s_nop 1
	v_cndmask_b32_e32 v36, v37, v36, vcc
	v_mov_b32_e32 v37, 0x43180000
	v_fmamk_f32 v36, v36, 0x41833333, v37
	v_div_scale_f32 v37, s[10:11], v188, v188, v36
	v_rcp_f32_e32 v38, v37
	s_nop 0
	v_fma_f32 v39, -v37, v38, 1.0
	v_fmac_f32_e32 v38, v39, v38
	v_div_scale_f32 v39, vcc, v36, v188, v36
	v_mul_f32_e32 v40, v39, v38
	v_fma_f32 v41, -v37, v40, v39
	v_fmac_f32_e32 v40, v41, v38
	v_fma_f32 v37, -v37, v40, v39
	v_div_fmas_f32 v37, v37, v38, v40
	v_div_fixup_f32 v36, v37, v188, v36
	v_cvt_f32_i32_e32 v37, v223
	v_sub_f32_e32 v36, v37, v36
	s_nop 1
	v_mov_b32_dpp v37, v36 quad_perm:[1,0,3,2] row_mask:0xf bank_mask:0xf bound_ctrl:1
	v_max_f32_e32 v37, v37, v37
	v_min_f32_e32 v36, v36, v37
	s_nop 1
	v_mov_b32_dpp v37, v36 quad_perm:[2,3,0,1] row_mask:0xf bank_mask:0xf bound_ctrl:1
	v_max_f32_e32 v37, v37, v37
	v_min_f32_e32 v36, v36, v37
	s_nop 1
	v_mov_b32_dpp v37, v36 row_half_mirror row_mask:0xf bank_mask:0xf bound_ctrl:1
	v_max_f32_e32 v37, v37, v37
	v_min_f32_e32 v36, v36, v37
	s_nop 1
	v_mov_b32_dpp v37, v36 row_mirror row_mask:0xf bank_mask:0xf bound_ctrl:1
	v_max_f32_e32 v37, v37, v37
	v_min_f32_e32 v36, v36, v37
	ds_swizzle_b32 v37, v36 offset:swizzle(SWAP,16)
	s_and_saveexec_b64 s[10:11], s[38:39]
	s_cbranch_execz .LBB0_308
	s_waitcnt lgkmcnt(0)
	v_max_f32_e32 v37, v37, v37
	v_max_f32_e32 v36, v36, v36
	v_min_f32_e32 v36, v36, v37
	v_mov_b32_e32 v37, s85
	ds_write_b32 v37, v36 offset:64

.LBB0_477:
	s_or_b64 exec, exec, s[4:5]
	v_readlane_b32 s4, v255, 24
	s_waitcnt lgkmcnt(0)
	s_barrier
	v_mov_b32_e32 v1, s4
	ds_read_b32 v1, v1
	s_mov_b64 s[4:5], -1
	s_waitcnt lgkmcnt(0)
	s_barrier
	v_readfirstlane_b32 s6, v1
	s_cmpk_gt_i32 s6, 0x4f
	s_cbranch_scc1 .LBB0_472
	s_mul_hi_i32 s4, s6, 0x99999999
	s_lshr_b32 s5, s4, 31
	s_ashr_i32 s8, s4, 2
	s_mul_hi_i32 s4, s6, 0x66666667
	s_add_i32 s8, s8, s5
	s_lshr_b32 s5, s4, 31
	s_lshr_b32 s4, s4, 2
	s_add_i32 s4, s4, s5
	s_mul_i32 s4, s4, 10
	s_sub_i32 s4, s6, s4
	s_lshl_b32 s4, s4, 3
	v_readlane_b32 s5, v255, 52
	s_or_b32 s4, s4, s5
	s_mul_hi_i32 s5, s4, 0x66666667
	s_lshr_b32 s6, s5, 31
	s_ashr_i32 s5, s5, 1
	s_add_i32 s6, s5, s6
	v_mov_b32_e32 v165, v0
	s_mul_i32 s5, s6, 5
	s_add_i32 s12, s8, 7
	v_readfirstlane_b32 s28, v165
	s_sub_i32 s25, s4, s5
	s_ashr_i32 s9, s28, 1
	s_lshl_b32 s5, s12, 8
	s_andn2_b32 s9, s9, 31
	s_ashr_i32 s7, s6, 31
	s_lshl_b32 s13, s25, 23
	v_and_b32_e32 v1, 31, v165
	s_add_i32 s33, s9, s5
	s_lshl_b64 s[22:23], s[6:7], 11
	s_add_i32 s5, s13, 0x15800000
	v_readlane_b32 s20, v254, 52
	v_or_b32_e32 v2, s33, v1
	v_readlane_b32 s21, v254, 53
	s_add_u32 s10, s20, s5
	s_addc_u32 s11, s21, 0
	s_add_i32 s5, s13, 0x10800000
	v_ashrrev_i32_e32 v3, 31, v2
	s_add_u32 s18, s20, s5
	v_writelane_b32 v255, s22, 55
	v_bfe_u32 v166, v165, 5, 1
	s_addc_u32 s19, s21, 0
	v_lshl_add_u64 v[2:3], s[22:23], 0, v[2:3]
	v_lshlrev_b64 v[2:3], 8, v[2:3]
	v_lshl_add_u64 v[2:3], s[18:19], 0, v[2:3]
	v_lshlrev_b32_e32 v34, 4, v166
	v_lshlrev_b32_e32 v4, 3, v165
	v_lshl_add_u64 v[2:3], v[2:3], 0, v[34:35]
	v_and_b32_e32 v168, 0x78, v4
	global_load_dwordx4 v[4:7], v[2:3], off
	global_load_dwordx4 v[224:227], v[2:3], off offset:32
	global_load_dwordx4 v[228:231], v[2:3], off offset:64
	global_load_dwordx4 v[232:235], v[2:3], off offset:96
	global_load_dwordx4 v[236:239], v[2:3], off offset:128
	global_load_dwordx4 v[240:243], v[2:3], off offset:160
	global_load_dwordx4 v[244:247], v[2:3], off offset:192
	global_load_dwordx4 v[248:251], v[2:3], off offset:224
	s_ashr_i32 s5, s4, 31
	s_lshl_b64 s[4:5], s[4:5], 13
	s_add_i32 s13, s13, 0x13000000
	v_writelane_b32 v255, s23, 56
	s_add_u32 s13, s20, s13
	s_addc_u32 s19, s21, 0
	v_readlane_b32 s20, v255, 47
	v_and_b32_e32 v49, 32, v165
	v_readlane_b32 s21, v255, 48
	v_readlane_b32 s22, v255, 49
	v_readlane_b32 s23, v255, 50
	s_lshl_b64 s[6:7], s[6:7], 19
	s_add_u32 s10, s10, s6
	s_addc_u32 s11, s11, s7
	v_ashrrev_i32_e32 v167, 4, v165
	v_cmp_gt_i32_e64 s[38:39], 64, v165
	s_waitcnt vmcnt(7)
	v_lshlrev_b32_e32 v80, 16, v4
	v_and_b32_e32 v77, 0xffff0000, v4
	v_lshlrev_b32_e32 v74, 16, v5
	v_and_b32_e32 v72, 0xffff0000, v5
	v_lshlrev_b32_e32 v81, 16, v6
	v_and_b32_e32 v78, 0xffff0000, v6
	v_lshlrev_b32_e32 v75, 16, v7
	v_and_b32_e32 v73, 0xffff0000, v7
	v_mul_f32_e32 v8, v77, v77
	v_fmac_f32_e32 v8, v80, v80
	v_fmac_f32_e32 v8, v74, v74
	v_fmac_f32_e32 v8, v72, v72
	v_fmac_f32_e32 v8, v81, v81
	v_fmac_f32_e32 v8, v78, v78
	v_fmac_f32_e32 v8, v75, v75
	v_fmac_f32_e32 v8, v73, v73
	s_waitcnt vmcnt(6)
	v_lshlrev_b32_e32 v85, 16, v224
	v_and_b32_e32 v83, 0xffff0000, v224
	v_lshlrev_b32_e32 v79, 16, v225
	v_and_b32_e32 v71, 0xffff0000, v225
	v_lshlrev_b32_e32 v84, 16, v226
	v_and_b32_e32 v82, 0xffff0000, v226
	v_lshlrev_b32_e32 v76, 16, v227
	v_and_b32_e32 v64, 0xffff0000, v227
	v_fmac_f32_e32 v8, v85, v85
	v_fmac_f32_e32 v8, v83, v83
	v_fmac_f32_e32 v8, v79, v79
	v_fmac_f32_e32 v8, v71, v71
	v_fmac_f32_e32 v8, v84, v84
	v_fmac_f32_e32 v8, v82, v82
	v_fmac_f32_e32 v8, v76, v76
	v_fmac_f32_e32 v8, v64, v64
	s_waitcnt vmcnt(5)
	v_lshlrev_b32_e32 v70, 16, v228
	v_and_b32_e32 v68, 0xffff0000, v228
	v_lshlrev_b32_e32 v66, 16, v229
	v_and_b32_e32 v63, 0xffff0000, v229
	v_lshlrev_b32_e32 v69, 16, v230
	v_and_b32_e32 v67, 0xffff0000, v230
	v_lshlrev_b32_e32 v65, 16, v231
	v_and_b32_e32 v56, 0xffff0000, v231
	v_fmac_f32_e32 v8, v70, v70
	v_fmac_f32_e32 v8, v68, v68
	v_fmac_f32_e32 v8, v66, v66
	v_fmac_f32_e32 v8, v63, v63
	v_fmac_f32_e32 v8, v69, v69
	v_fmac_f32_e32 v8, v67, v67
	v_fmac_f32_e32 v8, v65, v65
	v_fmac_f32_e32 v8, v56, v56
	s_waitcnt vmcnt(4)
	v_lshlrev_b32_e32 v62, 16, v232
	v_and_b32_e32 v60, 0xffff0000, v232
	v_lshlrev_b32_e32 v58, 16, v233
	v_and_b32_e32 v55, 0xffff0000, v233
	v_lshlrev_b32_e32 v61, 16, v234
	v_and_b32_e32 v59, 0xffff0000, v234
	v_lshlrev_b32_e32 v57, 16, v235
	v_and_b32_e32 v47, 0xffff0000, v235
	v_fmac_f32_e32 v8, v62, v62
	v_fmac_f32_e32 v8, v60, v60
	v_fmac_f32_e32 v8, v58, v58
	v_fmac_f32_e32 v8, v55, v55
	v_fmac_f32_e32 v8, v61, v61
	v_fmac_f32_e32 v8, v59, v59
	v_fmac_f32_e32 v8, v57, v57
	v_fmac_f32_e32 v8, v47, v47
	s_waitcnt vmcnt(3)
	v_lshlrev_b32_e32 v54, 16, v236
	v_and_b32_e32 v52, 0xffff0000, v236
	v_lshlrev_b32_e32 v50, 16, v237
	v_and_b32_e32 v46, 0xffff0000, v237
	v_lshlrev_b32_e32 v53, 16, v238
	v_and_b32_e32 v51, 0xffff0000, v238
	v_lshlrev_b32_e32 v48, 16, v239
	v_and_b32_e32 v39, 0xffff0000, v239
	v_fmac_f32_e32 v8, v54, v54
	v_fmac_f32_e32 v8, v52, v52
	v_fmac_f32_e32 v8, v50, v50
	v_fmac_f32_e32 v8, v46, v46
	v_fmac_f32_e32 v8, v53, v53
	v_fmac_f32_e32 v8, v51, v51
	v_fmac_f32_e32 v8, v48, v48
	v_fmac_f32_e32 v8, v39, v39
	s_waitcnt vmcnt(2)
	v_lshlrev_b32_e32 v45, 16, v240
	v_and_b32_e32 v43, 0xffff0000, v240
	v_lshlrev_b32_e32 v41, 16, v241
	v_and_b32_e32 v38, 0xffff0000, v241
	v_lshlrev_b32_e32 v44, 16, v242
	v_and_b32_e32 v42, 0xffff0000, v242
	v_lshlrev_b32_e32 v40, 16, v243
	v_and_b32_e32 v37, 0xffff0000, v243
	v_fmac_f32_e32 v8, v45, v45
	v_fmac_f32_e32 v8, v43, v43
	v_fmac_f32_e32 v8, v41, v41
	v_fmac_f32_e32 v8, v38, v38
	v_fmac_f32_e32 v8, v44, v44
	v_fmac_f32_e32 v8, v42, v42
	v_fmac_f32_e32 v8, v40, v40
	v_fmac_f32_e32 v8, v37, v37
	s_waitcnt vmcnt(1)
	v_lshlrev_b32_e32 v36, 16, v244
	v_and_b32_e32 v32, 0xffff0000, v244
	v_lshlrev_b32_e32 v30, 16, v245
	v_and_b32_e32 v28, 0xffff0000, v245
	v_fmac_f32_e32 v8, v36, v36
	v_fmac_f32_e32 v8, v32, v32
	v_fmac_f32_e32 v8, v30, v30
	v_lshlrev_b32_e32 v33, 16, v246
	v_fmac_f32_e32 v8, v28, v28
	v_and_b32_e32 v31, 0xffff0000, v246
	v_fmac_f32_e32 v8, v33, v33
	v_lshlrev_b32_e32 v29, 16, v247
	v_fmac_f32_e32 v8, v31, v31
	v_and_b32_e32 v27, 0xffff0000, v247
	v_fmac_f32_e32 v8, v29, v29
	v_fmac_f32_e32 v8, v27, v27
	s_waitcnt vmcnt(0)
	v_lshlrev_b32_e32 v24, 16, v248
	v_and_b32_e32 v22, 0xffff0000, v248
	v_fmac_f32_e32 v8, v24, v24
	v_lshlrev_b32_e32 v20, 16, v249
	v_fmac_f32_e32 v8, v22, v22
	v_and_b32_e32 v18, 0xffff0000, v249
	v_fmac_f32_e32 v8, v20, v20
	v_lshlrev_b32_e32 v25, 16, v250
	v_fmac_f32_e32 v8, v18, v18
	v_and_b32_e32 v23, 0xffff0000, v250
	v_fmac_f32_e32 v8, v25, v25
	v_lshlrev_b32_e32 v21, 16, v251
	v_fmac_f32_e32 v8, v23, v23
	v_and_b32_e32 v19, 0xffff0000, v251
	v_fmac_f32_e32 v8, v21, v21
	v_fmac_f32_e32 v8, v19, v19
	v_mov_b32_e32 v2, v8
	s_nop 1
	v_permlane32_swap_b32_e32 v8, v2
	v_add_f32_e32 v2, v8, v2
	v_fmamk_f32 v2, v2, 0x3c000000, v214
	v_rsq_f32_e32 v2, v2
	s_nop 0
	v_mul_f32_e32 v26, 0x3e0293ee, v2
	global_load_dwordx4 v[2:5], v49, s[20:21] offset:16
	global_load_dwordx4 v[10:13], v49, s[20:21]
	global_load_dwordx4 v[6:9], v49, s[22:23] offset:16
	global_load_dwordx4 v[14:17], v49, s[22:23]
	s_waitcnt vmcnt(3)
	v_mul_f32_e32 v2, v2, v26
	v_mul_f32_e32 v3, v3, v26
	v_mul_f32_e32 v4, v4, v26
	s_waitcnt vmcnt(2)
	v_mul_f32_e32 v10, v10, v26
	s_waitcnt vmcnt(1)
	v_mul_f32_e32 v2, v6, v2
	v_mul_f32_e32 v6, v11, v26
	v_mul_f32_e32 v3, v7, v3
	v_mul_f32_e32 v7, v12, v26
	v_mul_f32_e32 v4, v8, v4
	v_mul_f32_e32 v8, v13, v26
	v_mul_f32_e32 v5, v5, v26
	s_waitcnt vmcnt(0)
	v_mul_f32_e32 v10, v14, v10
	v_mul_f32_e32 v6, v15, v6
	v_mul_f32_e32 v7, v16, v7
	v_mul_f32_e32 v8, v17, v8
	v_mul_f32_e32 v5, v9, v5
	v_mul_f32_e32 v10, v10, v80
	v_mul_f32_e32 v2, v2, v81
	v_mul_f32_e32 v6, v6, v77
	v_mul_f32_e32 v3, v3, v78
	v_mul_f32_e32 v7, v7, v74
	v_mul_f32_e32 v4, v4, v75
	v_mul_f32_e32 v8, v8, v72
	v_mul_f32_e32 v5, v5, v73
	v_cvt_pk_bf16_f32 v100, v10, v6
	v_cvt_pk_bf16_f32 v101, v7, v8
	v_cvt_pk_bf16_f32 v102, v2, v3
	v_cvt_pk_bf16_f32 v103, v4, v5
	global_load_dwordx4 v[2:5], v49, s[20:21] offset:80
	global_load_dwordx4 v[6:9], v49, s[20:21] offset:64
	global_load_dwordx4 v[10:13], v49, s[22:23] offset:80
	global_load_dwordx4 v[14:17], v49, s[22:23] offset:64
	s_waitcnt vmcnt(3)
	v_mul_f32_e32 v2, v26, v2
	s_waitcnt vmcnt(2)
	v_mul_f32_e32 v6, v26, v6
	v_mul_f32_e32 v7, v26, v7
	v_mul_f32_e32 v3, v26, v3
	v_mul_f32_e32 v8, v26, v8
	v_mul_f32_e32 v4, v26, v4
	v_mul_f32_e32 v9, v26, v9
	v_mul_f32_e32 v5, v26, v5
	s_waitcnt vmcnt(0)
	v_mul_f32_e32 v6, v6, v14
	v_mul_f32_e32 v2, v2, v10
	v_mul_f32_e32 v7, v7, v15
	v_mul_f32_e32 v3, v3, v11
	v_mul_f32_e32 v8, v8, v16
	v_mul_f32_e32 v4, v4, v12
	v_mul_f32_e32 v9, v9, v17
	v_mul_f32_e32 v5, v5, v13
	v_mul_f32_e32 v6, v6, v85
	v_mul_f32_e32 v2, v2, v84
	v_mul_f32_e32 v7, v7, v83
	v_mul_f32_e32 v3, v3, v82
	v_mul_f32_e32 v8, v8, v79
	v_mul_f32_e32 v4, v4, v76
	v_mul_f32_e32 v9, v9, v71
	v_mul_f32_e32 v5, v5, v64
	v_cvt_pk_bf16_f32 v104, v6, v7
	v_cvt_pk_bf16_f32 v105, v8, v9
	v_cvt_pk_bf16_f32 v106, v2, v3
	v_cvt_pk_bf16_f32 v107, v4, v5
	global_load_dwordx4 v[2:5], v49, s[20:21] offset:144
	global_load_dwordx4 v[6:9], v49, s[20:21] offset:128
	global_load_dwordx4 v[10:13], v49, s[22:23] offset:144
	global_load_dwordx4 v[14:17], v49, s[22:23] offset:128
	s_waitcnt vmcnt(3)
	v_mul_f32_e32 v2, v26, v2
	s_waitcnt vmcnt(2)
	v_mul_f32_e32 v6, v26, v6
	v_mul_f32_e32 v7, v26, v7
	v_mul_f32_e32 v3, v26, v3
	v_mul_f32_e32 v8, v26, v8
	v_mul_f32_e32 v4, v26, v4
	v_mul_f32_e32 v9, v26, v9
	v_mul_f32_e32 v5, v26, v5
	s_waitcnt vmcnt(0)
	v_mul_f32_e32 v6, v6, v14
	v_mul_f32_e32 v2, v2, v10
	v_mul_f32_e32 v7, v7, v15
	v_mul_f32_e32 v3, v3, v11
	v_mul_f32_e32 v8, v8, v16
	v_mul_f32_e32 v4, v4, v12
	v_mul_f32_e32 v9, v9, v17
	v_mul_f32_e32 v5, v5, v13
	v_mul_f32_e32 v6, v6, v70
	v_mul_f32_e32 v2, v2, v69
	v_mul_f32_e32 v7, v7, v68
	v_mul_f32_e32 v3, v3, v67
	v_mul_f32_e32 v8, v8, v66
	v_mul_f32_e32 v4, v4, v65
	v_mul_f32_e32 v9, v9, v63
	v_mul_f32_e32 v5, v5, v56
	v_cvt_pk_bf16_f32 v108, v6, v7
	v_cvt_pk_bf16_f32 v109, v8, v9
	v_cvt_pk_bf16_f32 v110, v2, v3
	v_cvt_pk_bf16_f32 v111, v4, v5
	global_load_dwordx4 v[2:5], v49, s[20:21] offset:208
	global_load_dwordx4 v[6:9], v49, s[20:21] offset:192
	global_load_dwordx4 v[10:13], v49, s[22:23] offset:208
	global_load_dwordx4 v[14:17], v49, s[22:23] offset:192
	s_waitcnt vmcnt(3)
	v_mul_f32_e32 v2, v26, v2
	s_waitcnt vmcnt(2)
	v_mul_f32_e32 v6, v26, v6
	v_mul_f32_e32 v7, v26, v7
	v_mul_f32_e32 v3, v26, v3
	v_mul_f32_e32 v8, v26, v8
	v_mul_f32_e32 v4, v26, v4
	v_mul_f32_e32 v9, v26, v9
	v_mul_f32_e32 v5, v26, v5
	s_waitcnt vmcnt(0)
	v_mul_f32_e32 v6, v6, v14
	v_mul_f32_e32 v2, v2, v10
	v_mul_f32_e32 v7, v7, v15
	v_mul_f32_e32 v3, v3, v11
	v_mul_f32_e32 v8, v8, v16
	v_mul_f32_e32 v4, v4, v12
	v_mul_f32_e32 v9, v9, v17
	v_mul_f32_e32 v5, v5, v13
	v_mul_f32_e32 v6, v6, v62
	v_mul_f32_e32 v2, v2, v61
	v_mul_f32_e32 v7, v7, v60
	v_mul_f32_e32 v3, v3, v59
	v_mul_f32_e32 v8, v8, v58
	v_mul_f32_e32 v4, v4, v57
	v_mul_f32_e32 v9, v9, v55
	v_mul_f32_e32 v5, v5, v47
	v_cvt_pk_bf16_f32 v112, v6, v7
	v_cvt_pk_bf16_f32 v113, v8, v9
	v_cvt_pk_bf16_f32 v114, v2, v3
	v_cvt_pk_bf16_f32 v115, v4, v5
	global_load_dwordx4 v[2:5], v49, s[20:21] offset:272
	global_load_dwordx4 v[6:9], v49, s[20:21] offset:256
	global_load_dwordx4 v[10:13], v49, s[22:23] offset:272
	global_load_dwordx4 v[14:17], v49, s[22:23] offset:256
	s_waitcnt vmcnt(3)
	v_mul_f32_e32 v2, v26, v2
	s_waitcnt vmcnt(2)
	v_mul_f32_e32 v6, v26, v6
	v_mul_f32_e32 v7, v26, v7
	v_mul_f32_e32 v3, v26, v3
	v_mul_f32_e32 v8, v26, v8
	v_mul_f32_e32 v4, v26, v4
	v_mul_f32_e32 v9, v26, v9
	v_mul_f32_e32 v5, v26, v5
	s_waitcnt vmcnt(0)
	v_mul_f32_e32 v6, v6, v14
	v_mul_f32_e32 v2, v2, v10
	v_mul_f32_e32 v7, v7, v15
	v_mul_f32_e32 v3, v3, v11
	v_mul_f32_e32 v8, v8, v16
	v_mul_f32_e32 v4, v4, v12
	v_mul_f32_e32 v9, v9, v17
	v_mul_f32_e32 v5, v5, v13
	v_mul_f32_e32 v6, v6, v54
	v_mul_f32_e32 v2, v2, v53
	v_mul_f32_e32 v7, v7, v52
	v_mul_f32_e32 v3, v3, v51
	v_mul_f32_e32 v8, v8, v50
	v_mul_f32_e32 v4, v4, v48
	v_mul_f32_e32 v9, v9, v46
	v_mul_f32_e32 v5, v5, v39
	v_cvt_pk_bf16_f32 v116, v6, v7
	v_cvt_pk_bf16_f32 v117, v8, v9
	v_cvt_pk_bf16_f32 v118, v2, v3
	v_cvt_pk_bf16_f32 v119, v4, v5
	global_load_dwordx4 v[2:5], v49, s[20:21] offset:336
	global_load_dwordx4 v[6:9], v49, s[20:21] offset:320
	global_load_dwordx4 v[10:13], v49, s[22:23] offset:336
	global_load_dwordx4 v[14:17], v49, s[22:23] offset:320
	s_waitcnt vmcnt(3)
	v_mul_f32_e32 v2, v26, v2
	s_waitcnt vmcnt(2)
	v_mul_f32_e32 v6, v26, v6
	v_mul_f32_e32 v7, v26, v7
	v_mul_f32_e32 v3, v26, v3
	v_mul_f32_e32 v8, v26, v8
	v_mul_f32_e32 v4, v26, v4
	v_mul_f32_e32 v9, v26, v9
	v_mul_f32_e32 v5, v26, v5
	s_waitcnt vmcnt(0)
	v_mul_f32_e32 v6, v6, v14
	v_mul_f32_e32 v2, v2, v10
	v_mul_f32_e32 v7, v7, v15
	v_mul_f32_e32 v3, v3, v11
	v_mul_f32_e32 v8, v8, v16
	v_mul_f32_e32 v4, v4, v12
	v_mul_f32_e32 v9, v9, v17
	v_mul_f32_e32 v5, v5, v13
	v_mul_f32_e32 v6, v6, v45
	v_mul_f32_e32 v2, v2, v44
	v_mul_f32_e32 v7, v7, v43
	v_mul_f32_e32 v3, v3, v42
	v_mul_f32_e32 v8, v8, v41
	v_mul_f32_e32 v4, v4, v40
	v_mul_f32_e32 v9, v9, v38
	v_mul_f32_e32 v5, v5, v37
	v_cvt_pk_bf16_f32 v120, v6, v7
	v_cvt_pk_bf16_f32 v121, v8, v9
	v_cvt_pk_bf16_f32 v122, v2, v3
	v_cvt_pk_bf16_f32 v123, v4, v5
	global_load_dwordx4 v[2:5], v49, s[20:21] offset:400
	global_load_dwordx4 v[6:9], v49, s[20:21] offset:384
	global_load_dwordx4 v[10:13], v49, s[22:23] offset:400
	global_load_dwordx4 v[14:17], v49, s[22:23] offset:384
	s_waitcnt vmcnt(3)
	v_mul_f32_e32 v2, v26, v2
	s_waitcnt vmcnt(2)
	v_mul_f32_e32 v6, v26, v6
	v_mul_f32_e32 v7, v26, v7
	v_mul_f32_e32 v3, v26, v3
	v_mul_f32_e32 v8, v26, v8
	v_mul_f32_e32 v4, v26, v4
	v_mul_f32_e32 v9, v26, v9
	v_mul_f32_e32 v5, v26, v5
	s_waitcnt vmcnt(0)
	v_mul_f32_e32 v6, v6, v14
	v_mul_f32_e32 v2, v2, v10
	v_mul_f32_e32 v7, v7, v15
	v_mul_f32_e32 v3, v3, v11
	v_mul_f32_e32 v8, v8, v16
	v_mul_f32_e32 v4, v4, v12
	v_mul_f32_e32 v9, v9, v17
	v_mul_f32_e32 v5, v5, v13
	v_mul_f32_e32 v6, v6, v36
	v_mul_f32_e32 v2, v2, v33
	v_mul_f32_e32 v7, v7, v32
	v_mul_f32_e32 v3, v3, v31
	v_mul_f32_e32 v8, v8, v30
	v_mul_f32_e32 v4, v4, v29
	v_mul_f32_e32 v9, v9, v28
	v_mul_f32_e32 v5, v5, v27
	v_cvt_pk_bf16_f32 v124, v6, v7
	v_cvt_pk_bf16_f32 v125, v8, v9
	v_cvt_pk_bf16_f32 v126, v2, v3
	v_cvt_pk_bf16_f32 v127, v4, v5
	global_load_dwordx4 v[2:5], v49, s[20:21] offset:464
	global_load_dwordx4 v[6:9], v49, s[20:21] offset:448
	global_load_dwordx4 v[10:13], v49, s[22:23] offset:464
	global_load_dwordx4 v[14:17], v49, s[22:23] offset:448
	v_readlane_b32 s20, v252, 57
	v_readlane_b32 s21, v252, 58
	s_add_u32 s22, s20, s4
	s_addc_u32 s23, s21, s5
	s_add_u32 s18, s13, s6
	s_addc_u32 s19, s19, s7
	s_lshl_b32 s24, s12, 2
	s_or_b32 s6, s24, 3
	s_lshl_b32 s7, s6, 6
	s_movk_i32 s4, 0x2000
	s_waitcnt vmcnt(3)
	v_mul_f32_e32 v2, v26, v2
	s_waitcnt vmcnt(2)
	v_mul_f32_e32 v6, v26, v6
	s_waitcnt vmcnt(1)
	v_mul_f32_e32 v2, v2, v10
	v_mul_f32_e32 v7, v26, v7
	v_mul_f32_e32 v3, v26, v3
	v_mul_f32_e32 v8, v26, v8
	v_mul_f32_e32 v9, v26, v9
	s_waitcnt vmcnt(0)
	v_mul_f32_e32 v6, v6, v14
	v_mul_f32_e32 v2, v2, v25
	v_mul_f32_e32 v7, v7, v15
	v_mul_f32_e32 v3, v3, v11
	v_mul_f32_e32 v8, v8, v16
	v_mul_f32_e32 v9, v9, v17
	v_mul_f32_e32 v6, v6, v24
	v_mul_f32_e32 v7, v7, v22
	v_mul_f32_e32 v3, v3, v23
	v_mul_f32_e32 v8, v8, v20
	v_mul_f32_e32 v9, v9, v18
	v_cvt_pk_bf16_f32 v128, v6, v7
	v_cvt_pk_bf16_f32 v129, v8, v9
	v_cvt_pk_bf16_f32 v130, v2, v3
	v_add_u32_e32 v2, s7, v167
	v_ashrrev_i32_e32 v3, 31, v2
	v_mul_f32_e32 v4, v26, v4
	v_mul_f32_e32 v5, v26, v5
	v_lshlrev_b64 v[10:11], 8, v[2:3]
	v_mul_f32_e32 v4, v4, v12
	v_mul_f32_e32 v5, v5, v13
	v_lshl_or_b32 v10, v168, 1, v10
	v_mul_f32_e32 v4, v4, v21
	v_mul_f32_e32 v5, v5, v19
	v_lshl_add_u64 v[6:7], s[18:19], 0, v[10:11]
	v_lshl_add_u64 v[14:15], s[10:11], 0, v[10:11]
	v_cvt_pk_bf16_f32 v131, v4, v5
	global_load_dwordx4 v[2:5], v[6:7], off
	global_load_dwordx4 v[10:13], v[14:15], off
	v_add_co_u32_e32 v6, vcc, s4, v6
	s_nop 1
	v_addc_co_u32_e32 v7, vcc, 0, v7, vcc
	v_add_co_u32_e32 v14, vcc, 0x2000, v14
	global_load_dwordx4 v[6:9], v[6:7], off
	s_nop 0
	v_addc_co_u32_e32 v15, vcc, 0, v15, vcc
	global_load_dwordx4 v[14:17], v[14:15], off
	s_and_saveexec_b64 s[4:5], s[38:39]
	s_cbranch_execz .LBB0_480
	v_add_u32_e32 v18, s7, v165
	v_ashrrev_i32_e32 v19, 31, v18
	v_lshl_add_u64 v[18:19], v[18:19], 2, s[22:23]
	global_load_dword v169, v[18:19], off
